# waves 4-7 priority raise also at rowB and rowC entry (persists until the next GEMM's own toggles)
# baseline (speedup 1.0000x reference)
; #define GAS __attribute__((address_space(1)))
; #define ROWB_LOAD(mm, X, M_) do { const GAS f32x4* x_ = (const GAS f32x4*)xrow(A, layer, (mm)); const GAS f32x4* mx_ = (const GAS f32x4*)(A->ws + WS_MIX) + (size_t)(mm) * (DM / 4); \
;         _Pragma("unroll") for (int j = 0; j < 8; ++j) { X[j] = __builtin_nontemporal_load(&x_[64 * j + lane]); if ((mm) < MP) M_[j] = __builtin_nontemporal_load(&mx_[64 * j + lane]); } } while (0)
; __device__ __forceinline__ void rowB_phase(ArgP A, int layer, int lane, int wave, int bid, int G) {
;     const GAS float* gpost = A->in[9] + layer * DM; const GAS float* gpre = A->in[10] + layer * DM;
;     const int gw_ = bid * NWAVES + wave, NW_ = G * NWAVES; int ri = 0; int m = row_of(gw_, NW_, 0);
;     f32x4 xv[8], mv[8];
;     ...
;     if (m >= 0) ROWB_LOAD(m, xv, mv);
.LBB0_1522:
	s_cmp_le_i32 s74, s18
	s_cselect_b64 s[8:9], -1, 0
	s_and_b64 s[0:1], s[8:9], s[4:5]
	s_andn2_b64 vcc, exec, s[0:1]
	s_cbranch_vccnz .LBB0_1572
	v_mov_b32_e32 v0, v195
	s_mov_b64 s[12:13], s[68:69]
	v_readfirstlane_b32 s0, v0
	s_cmpk_lt_u32 s0, 0x100
	s_cbranch_scc1 .Lprio_rb
	s_setprio 1
.Lprio_rb:
	s_ashr_i32 s14, s0, 6
	v_readlane_b32 s0, v253, 30
	s_add_i32 s14, s14, s0
	s_cmpk_lt_i32 s14, 0x2200
	s_cselect_b32 s2, s14, -1
	s_cmpk_gt_i32 s14, 0x1ff
	s_cselect_b64 s[10:11], -1, 0
	s_add_i32 s0, s14, 0x2000
	s_cmpk_lt_i32 s14, 0x200
	s_cselect_b32 s3, s0, s14
	v_readlane_b32 s0, v251, 9
	v_readlane_b32 s1, v251, 10
	s_and_b64 s[0:1], s[0:1], exec
	s_cselect_b32 s18, s3, s2
	v_and_b32_e32 v160, 63, v0
	s_cmp_gt_i32 s18, -1
	v_or_b32_e32 v5, 0x100, v160
	v_or_b32_e32 v4, 0x140, v160
	v_or_b32_e32 v3, 0x180, v160
	v_or_b32_e32 v2, 0x1c0, v160
	s_cselect_b64 s[0:1], -1, 0
	s_cmp_lt_i32 s18, 0
	v_lshlrev_b32_e32 v16, 4, v160
	s_cbranch_scc1 .LBB0_1528
	v_sub_co_u32_e32 v0, vcc, s18, v235
	s_and_b64 s[2:3], vcc, exec
	v_readfirstlane_b32 s2, v0
	s_cselect_b32 s4, s18, s2
	v_readlane_b32 s2, v254, 13
	v_readlane_b32 s3, v254, 14
	s_cselect_b32 s5, 0, 8
	s_and_b64 s[2:3], exec, s[2:3]
	s_cselect_b32 s2, s5, 0x130
	s_cselect_b32 s82, s4, s18
	s_add_u32 s2, s12, s2
	s_addc_u32 s3, s13, 0
	s_load_dwordx2 s[2:3], s[2:3], 0x0
	s_lshl_b64 s[4:5], s[82:83], 13
	s_load_dwordx2 s[6:7], s[12:13], 0x138
	s_mov_b32 s19, s83
	v_cndmask_b32_e64 v1, 0, 1, vcc
	s_waitcnt lgkmcnt(0)
	s_add_u32 s2, s2, s4
	s_addc_u32 s3, s3, s5
	global_load_dwordx4 v[118:121], v16, s[2:3] nt
	s_lshl_b64 s[4:5], s[18:19], 13
	s_add_u32 s4, s6, s4
	s_addc_u32 s5, s7, s5
	s_add_u32 s6, s4, 0x15800000
	s_addc_u32 s7, s5, 0
	v_mov_b32_e32 v126, 0
	v_cmp_ne_u32_e64 s[4:5], 1, v1
	s_and_b64 vcc, exec, s[4:5]
	v_mov_b32_e32 v127, v126
	v_mov_b32_e32 v128, v126
	v_mov_b32_e32 v129, v126
	s_cbranch_vccnz .LBB0_1526
	global_load_dwordx4 v[126:129], v16, s[6:7] nt

; #define GAS __attribute__((address_space(1)))
; #define ROWC_LOAD(mm, X, M_) do { const GAS f32x4* x_ = (const GAS f32x4*)(A->ws + WS_XF) + (size_t)(mm) * (DM / 4); const GAS f32x4* mx_ = (const GAS f32x4*)(A->ws + WS_MIX) + (size_t)(mm) * (DM / 4); \
;         _Pragma("unroll") for (int j = 0; j < 8; ++j) { X[j] = __builtin_nontemporal_load(&x_[64 * j + lane]); if ((mm) < MP) M_[j] = __builtin_nontemporal_load(&mx_[64 * j + lane]); } } while (0)
; __device__ __forceinline__ void rowC_phase(ArgP A, int layer, int lane, int wave, int bid, int G) {
;     const GAS float* gpost = A->in[11] + layer * DM;
;     const int gw_ = bid * NWAVES + wave, NW_ = G * NWAVES; int ri = 0; int m = row_of(gw_, NW_, 0);
;     f32x4 xv[8], mv[8];
;     ...
;     if (m >= 0) ROWC_LOAD(m, xv, mv);
.LBB0_1826:
	s_cmp_le_i32 s74, s18
	s_cselect_b64 s[6:7], -1, 0
	s_and_b64 s[0:1], s[6:7], s[4:5]
	s_andn2_b64 vcc, exec, s[0:1]
	s_cbranch_vccnz .LBB0_1880
	v_mov_b32_e32 v0, v195
	v_cndmask_b32_e64 v1, 0, 1, s[76:77]
	v_readfirstlane_b32 s0, v0
	s_cmpk_lt_u32 s0, 0x100
	s_cbranch_scc1 .Lprio_rc
	s_setprio 1
.Lprio_rc:
	s_ashr_i32 s18, s0, 6
	v_readlane_b32 s0, v253, 30
	s_mov_b64 s[8:9], s[68:69]
	s_add_i32 s18, s18, s0
	v_cmp_ne_u32_e64 s[42:43], 1, v1
	s_andn2_b64 vcc, exec, s[76:77]
	s_mov_b64 s[2:3], -1
	s_cbranch_vccnz .LBB0_1829
	s_cmpk_lt_i32 s18, 0x2200
	s_cselect_b32 s16, s18, -1
	s_mov_b64 s[2:3], 0
